# attention tile loop edge: next tile's K/Q fragment reads issued immediately after the tile barrier, ahead of loop bookkeeping and DMA issue
# speedup vs baseline: 1.0050x; 1.0050x over previous
; #define SB() __builtin_amdgcn_sched_barrier(0)
; #define EXPACK(sc_, rbq_, p0_, p1_) do { float ps_ = 0.f; \
;                 _Pragma("unroll") for (int r = 0; r < 16; ++r) { sc_[r] = __builtin_amdgcn_exp2f(SHIFT ? sc_[r] - bound2 : sc_[r]); ps_ += sc_[r]; } \
;                 lsum[rbq_] += ps_; p0_ = pack8(sc_, 0); p1_ = pack8(sc_, 1); } while (0)
; #define BLOAD(B_, ks_) do { asm volatile("" : "+v"(v0l)); _Pragma("unroll") for (int cb = 0; cb < 4; ++cb) B_[cb] = BFRAG(ks_, cb); SB(); } while (0)
; #define PVMMA(B_, pA_, pB_) do { _Pragma("unroll") for (int cb = 0; cb < 4; ++cb) { o[0][cb] = MFMA32(pA_, B_[cb], o[0][cb]); o[1][cb] = MFMA32(pB_, B_[cb], o[1][cb]); } } while (0)
; template <bool SHIFT> DI void phase_attn2(const Params& p, const Grp& G, int layer, LAS unsigned char* lds, int tid, int wave, int lane, int vcu, bool dry) {
;     ...
;             {
;                 f32x16 s0, s1; bf16x8 pa00, pa01, pa10, pa11; bf16x8 kfs[4], qfs[4];
;                 CHAIN(s0, 0, 0, true, true); CHAIN(s1, 0, 1, false, true);
;                 EXPACK(s0, 0, pa00, pa01); EXPACK(s1, 1, pa10, pa11);
;                 SB();
;                 CHAIN(s1, 1, 1, true, false); CHAIN(s0, 1, 0, false, true);
;                 bf16x8 pb00, pb01, pb10, pb11; bf16x8 B[4];
;                 BLOAD(B, 0);
;                 PVMMA(B, pa00, pa10); EXPACK(s0, 0, pb00, pb01);
;                 SB();
;                 BLOAD(B, 1);
;                 PVMMA(B, pa01, pa11); EXPACK(s1, 1, pb10, pb11);
;                 SB();
;                 BLOAD(B, 2);
;                 PVMMA(B, pb00, pb10);
;                 SB();
;                 BLOAD(B, 3);
;                 PVMMA(B, pb01, pb11);
;                 SB();
;             }
.LBB0_378:
	s_waitcnt lgkmcnt(0)
	v_mfma_f32_32x32x16_bf16 v[144:159], v[128:131], v[132:135], 0
	v_mfma_f32_32x32x16_bf16 v[144:159], v[160:163], v[136:139], v[144:159]
	v_mfma_f32_32x32x16_bf16 v[144:159], v[166:169], v[140:143], v[144:159]
	v_mfma_f32_32x32x16_bf16 v[144:159], v[170:173], v[174:177], v[144:159]
	ds_read_b128 v[174:177], v222 offset:4096
	ds_read_b128 v[178:181], v222 offset:5120
	ds_read_b128 v[182:185], v222 offset:6144
	ds_read_b128 v[224:227], v222 offset:7168
	s_waitcnt lgkmcnt(0)
	v_mfma_f32_32x32x16_bf16 v[128:143], v[128:131], v[174:177], 0
	v_mfma_f32_32x32x16_bf16 v[128:143], v[160:163], v[178:181], v[128:143]
	v_mfma_f32_32x32x16_bf16 v[128:143], v[166:169], v[182:185], v[128:143]
	v_mfma_f32_32x32x16_bf16 v[128:143], v[170:173], v[224:227], v[128:143]
	ds_read_b128 v[170:173], v236 offset:8192
	ds_read_b128 v[228:231], v237 offset:8192
	ds_read_b128 v[232:235], v238 offset:8192
	v_exp_f32_e32 v144, v144
	v_exp_f32_e32 v145, v145
	v_exp_f32_e32 v146, v146
	v_exp_f32_e32 v147, v147
	v_exp_f32_e32 v148, v148
	v_exp_f32_e32 v149, v149
	v_exp_f32_e32 v150, v150
	v_exp_f32_e32 v188, v151
	v_exp_f32_e32 v208, v152
	v_exp_f32_e32 v206, v153
	v_exp_f32_e32 v204, v154
	v_exp_f32_e32 v202, v155
	v_exp_f32_e32 v200, v156
	v_exp_f32_e32 v198, v157
	v_exp_f32_e32 v196, v158
	v_exp_f32_e32 v190, v159
	v_exp_f32_e32 v189, v135
	v_add_f32_e32 v135, v145, v144
	v_exp_f32_e32 v128, v128
	v_exp_f32_e32 v129, v129
	v_exp_f32_e32 v130, v130
	v_exp_f32_e32 v131, v131
	v_exp_f32_e32 v132, v132
	v_exp_f32_e32 v133, v133
	v_exp_f32_e32 v134, v134
	v_add_f32_e32 v135, v146, v135
	v_add_f32_e32 v135, v147, v135
	v_add_f32_e32 v135, v148, v135
	v_add_f32_e32 v135, v149, v135
	v_cvt_pk_bf16_f32 v160, v144, v145
	v_cvt_pk_bf16_f32 v161, v146, v147
	v_cvt_pk_bf16_f32 v162, v148, v149
	v_cvt_pk_bf16_f32 v163, v150, v188
	v_exp_f32_e32 v209, v136
	v_exp_f32_e32 v207, v137
	v_exp_f32_e32 v205, v138
	v_exp_f32_e32 v203, v139
	v_exp_f32_e32 v201, v140
	v_exp_f32_e32 v199, v141
	v_exp_f32_e32 v197, v142
	v_exp_f32_e32 v191, v143
	v_add_f32_e32 v210, v150, v135
	v_cvt_pk_bf16_f32 v166, v128, v129
	v_cvt_pk_bf16_f32 v167, v130, v131
	v_cvt_pk_bf16_f32 v168, v132, v133
	v_cvt_pk_bf16_f32 v169, v134, v189
	ds_read_b128 v[144:147], v217 offset:8192
	v_add_f32_e32 v128, v129, v128
	v_add_f32_e32 v128, v130, v128
	v_add_f32_e32 v128, v131, v128
	v_add_f32_e32 v128, v132, v128
	v_add_f32_e32 v128, v133, v128
	v_add_f32_e32 v211, v134, v128
	s_waitcnt lgkmcnt(0)
	v_mfma_f32_32x32x16_bf16 v[128:143], v[144:147], v[174:177], 0
	v_mfma_f32_32x32x16_bf16 v[128:143], v[170:173], v[178:181], v[128:143]
	v_mfma_f32_32x32x16_bf16 v[128:143], v[228:231], v[182:185], v[128:143]
	v_mfma_f32_32x32x16_bf16 v[128:143], v[232:235], v[224:227], v[128:143]
	ds_read_b128 v[148:151], v222
	ds_read_b128 v[174:177], v222 offset:1024
	ds_read_b128 v[178:181], v222 offset:2048
	ds_read_b128 v[182:185], v222 offset:3072
	s_waitcnt lgkmcnt(0)
	v_mfma_f32_32x32x16_bf16 v[144:159], v[144:147], v[148:151], 0
	v_mfma_f32_32x32x16_bf16 v[144:159], v[170:173], v[174:177], v[144:159]
	v_mfma_f32_32x32x16_bf16 v[144:159], v[228:231], v[178:181], v[144:159]
	v_mfma_f32_32x32x16_bf16 v[144:159], v[232:235], v[182:185], v[144:159]
	s_nop 4
	ds_read_b64_tr_b16 v[170:171], v218 offset:16384
	ds_read_b64_tr_b16 v[172:173], v239 offset:18432
	ds_read_b64_tr_b16 v[174:175], v240 offset:16384
	ds_read_b64_tr_b16 v[176:177], v241 offset:18432
	ds_read_b64_tr_b16 v[178:179], v248 offset:16384
	ds_read_b64_tr_b16 v[180:181], v249 offset:18432
	ds_read_b64_tr_b16 v[182:183], v250 offset:16384
	ds_read_b64_tr_b16 v[184:185], v251 offset:18432
	v_exp_f32_e32 v144, v144
	s_waitcnt lgkmcnt(6)
	v_mfma_f32_32x32x16_bf16 v[112:127], v[160:163], v[170:173], v[112:127]
	v_exp_f32_e32 v145, v145
	v_exp_f32_e32 v146, v146
	v_exp_f32_e32 v147, v147
	v_exp_f32_e32 v148, v148
	v_exp_f32_e32 v149, v149
	v_mfma_f32_32x32x16_bf16 v[0:15], v[166:169], v[170:173], v[0:15]
	v_exp_f32_e32 v170, v151
	v_exp_f32_e32 v172, v154
	s_waitcnt lgkmcnt(4)
	v_mfma_f32_32x32x16_bf16 v[96:111], v[160:163], v[174:177], v[96:111]
	v_mfma_f32_32x32x16_bf16 v[16:31], v[166:169], v[174:177], v[16:31]
	v_exp_f32_e32 v174, v153
	v_exp_f32_e32 v176, v156
	s_waitcnt lgkmcnt(2)
	v_mfma_f32_32x32x16_bf16 v[80:95], v[160:163], v[178:181], v[80:95]
	v_mfma_f32_32x32x16_bf16 v[32:47], v[166:169], v[178:181], v[32:47]
	v_exp_f32_e32 v178, v155
	v_exp_f32_e32 v180, v158
	s_waitcnt lgkmcnt(0)
	v_mfma_f32_32x32x16_bf16 v[64:79], v[160:163], v[182:185], v[64:79]
	v_add_f32_e32 v160, v145, v144
	v_add_f32_e32 v160, v146, v160
	v_add_f32_e32 v160, v147, v160
	v_add_f32_e32 v160, v148, v160
	v_add_f32_e32 v186, v149, v160
	v_cvt_pk_bf16_f32 v144, v144, v145
	v_mfma_f32_32x32x16_bf16 v[48:63], v[166:169], v[182:185], v[48:63]
	v_exp_f32_e32 v166, v150
	v_exp_f32_e32 v168, v152
	v_exp_f32_e32 v182, v157
	v_exp_f32_e32 v184, v159
	v_cvt_pk_bf16_f32 v145, v146, v147
	v_cvt_pk_bf16_f32 v146, v148, v149
	s_nop 0
	ds_read_b64_tr_b16 v[160:161], v218 offset:20480
	ds_read_b64_tr_b16 v[162:163], v239 offset:22528
	ds_read_b64_tr_b16 v[156:157], v240 offset:20480
	ds_read_b64_tr_b16 v[158:159], v241 offset:22528
	ds_read_b64_tr_b16 v[152:153], v248 offset:20480
	ds_read_b64_tr_b16 v[154:155], v249 offset:22528
	ds_read_b64_tr_b16 v[148:149], v250 offset:20480
	ds_read_b64_tr_b16 v[150:151], v251 offset:22528
	v_exp_f32_e32 v223, v128
	v_exp_f32_e32 v224, v129
	v_exp_f32_e32 v225, v130
	v_exp_f32_e32 v226, v131
	v_exp_f32_e32 v227, v132
	v_add_f32_e32 v128, v224, v223
	v_exp_f32_e32 v228, v133
	v_exp_f32_e32 v167, v134
	v_exp_f32_e32 v171, v135
	v_cvt_pk_bf16_f32 v132, v208, v206
	v_cvt_pk_bf16_f32 v133, v204, v202
	v_cvt_pk_bf16_f32 v134, v200, v198
	v_cvt_pk_bf16_f32 v135, v196, v190
	v_add_f32_e32 v128, v225, v128
	v_exp_f32_e32 v169, v136
	v_exp_f32_e32 v175, v137
	v_exp_f32_e32 v173, v138
	v_exp_f32_e32 v179, v139
	v_cvt_pk_bf16_f32 v136, v209, v207
	v_cvt_pk_bf16_f32 v137, v205, v203
	v_cvt_pk_bf16_f32 v138, v201, v199
	v_cvt_pk_bf16_f32 v139, v197, v191
	v_add_f32_e32 v128, v226, v128
	v_add_f32_e32 v128, v227, v128
	v_add_f32_e32 v187, v228, v128
	v_pk_add_f32 v[128:129], v[188:189], v[210:211]
	s_waitcnt lgkmcnt(6)
; #define SB() __builtin_amdgcn_sched_barrier(0)
; #define EXPACK(sc_, rbq_, p0_, p1_) do { float ps_ = 0.f; \
;                 _Pragma("unroll") for (int r = 0; r < 16; ++r) { sc_[r] = __builtin_amdgcn_exp2f(SHIFT ? sc_[r] - bound2 : sc_[r]); ps_ += sc_[r]; } \
;                 lsum[rbq_] += ps_; p0_ = pack8(sc_, 0); p1_ = pack8(sc_, 1); } while (0)
; #define BLOAD(B_, ks_) do { asm volatile("" : "+v"(v0l)); _Pragma("unroll") for (int cb = 0; cb < 4; ++cb) B_[cb] = BFRAG(ks_, cb); SB(); } while (0)
; #define PVMMA(B_, pA_, pB_) do { _Pragma("unroll") for (int cb = 0; cb < 4; ++cb) { o[0][cb] = MFMA32(pA_, B_[cb], o[0][cb]); o[1][cb] = MFMA32(pB_, B_[cb], o[1][cb]); } } while (0)
; template <bool SHIFT> DI void phase_attn2(const Params& p, const Grp& G, int layer, LAS unsigned char* lds, int tid, int wave, int lane, int vcu, bool dry) {
;     ...
;                 PVMMA(B, pa00, pa10); EXPACK(s0, 0, pb00, pb01);
;                 SB();
;                 BLOAD(B, 1);
;                 PVMMA(B, pa01, pa11); EXPACK(s1, 1, pb10, pb11);
;                 SB();
;                 BLOAD(B, 2);
;                 PVMMA(B, pb00, pb10);
;                 SB();
;                 BLOAD(B, 3);
;                 PVMMA(B, pb01, pb11);
;                 SB();
;             }
;     ...
;             asm volatile("s_waitcnt vmcnt(0)" ::: "memory");
;             __syncthreads();
	v_mfma_f32_32x32x16_bf16 v[112:127], v[132:135], v[160:163], v[112:127]
	v_add_f32_e64 v128, v208, v128
	v_add_f32_e64 v129, v209, v129
	v_exp_f32_e32 v177, v140
	v_pk_add_f32 v[128:129], v[206:207], v[128:129]
	v_exp_f32_e32 v183, v141
	v_pk_add_f32 v[128:129], v[204:205], v[128:129]
	v_exp_f32_e32 v181, v142
	v_pk_add_f32 v[128:129], v[202:203], v[128:129]
	s_waitcnt lgkmcnt(4)
	v_mfma_f32_32x32x16_bf16 v[96:111], v[132:135], v[156:159], v[96:111]
	v_exp_f32_e32 v185, v143
	v_pk_add_f32 v[128:129], v[200:201], v[128:129]
	v_cvt_pk_bf16_f32 v147, v166, v170
	v_pk_add_f32 v[128:129], v[198:199], v[128:129]
	v_cvt_pk_bf16_f32 v130, v176, v182
	v_pk_add_f32 v[128:129], v[196:197], v[128:129]
	v_cvt_pk_bf16_f32 v131, v180, v184
	s_waitcnt lgkmcnt(2)
	v_mfma_f32_32x32x16_bf16 v[80:95], v[132:135], v[152:155], v[80:95]
	v_add_f32_e64 v128, v190, v128
	v_add_f32_e64 v129, v191, v129
	v_add_f32_e64 v140, v164, v128
	v_add_f32_e64 v141, v165, v129
	v_cvt_pk_bf16_f32 v128, v168, v174
	v_cvt_pk_bf16_f32 v129, v172, v178
	s_waitcnt lgkmcnt(0)
	v_mfma_f32_32x32x16_bf16 v[64:79], v[132:135], v[148:151], v[64:79]
	v_add_f32_e64 v132, v166, v186
	v_add_f32_e64 v133, v167, v187
	v_cvt_pk_bf16_f32 v134, v227, v228
	v_add_f32_e64 v132, v170, v132
	v_add_f32_e64 v133, v171, v133
	v_cvt_pk_bf16_f32 v135, v167, v171
	v_pk_add_f32 v[132:133], v[168:169], v[132:133]
	s_nop 0
	v_pk_add_f32 v[132:133], v[174:175], v[132:133]
	v_mfma_f32_32x32x16_bf16 v[0:15], v[136:139], v[160:163], v[0:15]
	v_add_f32_e64 v132, v172, v132
	v_add_f32_e64 v133, v173, v133
	v_add_f32_e64 v132, v178, v132
	v_add_f32_e64 v133, v179, v133
	v_add_f32_e64 v132, v176, v132
	v_add_f32_e64 v133, v177, v133
	v_pk_add_f32 v[132:133], v[182:183], v[132:133]
	v_mfma_f32_32x32x16_bf16 v[16:31], v[136:139], v[156:159], v[16:31]
	v_add_f32_e64 v132, v180, v132
	v_add_f32_e64 v133, v181, v133
	v_add_f32_e64 v142, v184, v132
	v_add_f32_e64 v143, v185, v133
	v_cvt_pk_bf16_f32 v132, v223, v224
	v_cvt_pk_bf16_f32 v133, v225, v226
	v_mfma_f32_32x32x16_bf16 v[32:47], v[136:139], v[152:155], v[32:47]
	v_mfma_f32_32x32x16_bf16 v[48:63], v[136:139], v[148:151], v[48:63]
	v_cvt_pk_bf16_f32 v136, v169, v175
	v_cvt_pk_bf16_f32 v137, v173, v179
	v_cvt_pk_bf16_f32 v138, v177, v183
	v_cvt_pk_bf16_f32 v139, v181, v185
	s_nop 0
	ds_read_b64_tr_b16 v[148:149], v218 offset:24576
	ds_read_b64_tr_b16 v[150:151], v239 offset:26624
	ds_read_b64_tr_b16 v[152:153], v240 offset:24576
	ds_read_b64_tr_b16 v[154:155], v241 offset:26624
	ds_read_b64_tr_b16 v[156:157], v248 offset:24576
	ds_read_b64_tr_b16 v[158:159], v249 offset:26624
	ds_read_b64_tr_b16 v[160:161], v250 offset:24576
	ds_read_b64_tr_b16 v[162:163], v251 offset:26624
	s_waitcnt lgkmcnt(6)
	v_mfma_f32_32x32x16_bf16 v[112:127], v[144:147], v[148:151], v[112:127]
	v_add_f32_e64 v164, v140, v142
	v_add_f32_e64 v165, v141, v143
	v_mfma_f32_32x32x16_bf16 v[0:15], v[132:135], v[148:151], v[0:15]
	s_waitcnt lgkmcnt(4)
	v_mfma_f32_32x32x16_bf16 v[96:111], v[144:147], v[152:155], v[96:111]
	v_mfma_f32_32x32x16_bf16 v[16:31], v[132:135], v[152:155], v[16:31]
	s_waitcnt lgkmcnt(2)
	v_mfma_f32_32x32x16_bf16 v[80:95], v[144:147], v[156:159], v[80:95]
	v_mfma_f32_32x32x16_bf16 v[32:47], v[132:135], v[156:159], v[32:47]
	s_waitcnt lgkmcnt(0)
	v_mfma_f32_32x32x16_bf16 v[64:79], v[144:147], v[160:163], v[64:79]
	v_mfma_f32_32x32x16_bf16 v[48:63], v[132:135], v[160:163], v[48:63]
	s_nop 0
	ds_read_b64_tr_b16 v[132:133], v218 offset:28672
	ds_read_b64_tr_b16 v[134:135], v239 offset:30720
	ds_read_b64_tr_b16 v[140:141], v240 offset:28672
	ds_read_b64_tr_b16 v[142:143], v241 offset:30720
	ds_read_b64_tr_b16 v[144:145], v248 offset:28672
	ds_read_b64_tr_b16 v[146:147], v249 offset:30720
	ds_read_b64_tr_b16 v[148:149], v250 offset:28672
	ds_read_b64_tr_b16 v[150:151], v251 offset:30720
	s_waitcnt lgkmcnt(6)
	v_mfma_f32_32x32x16_bf16 v[112:127], v[128:131], v[132:135], v[112:127]
	v_mfma_f32_32x32x16_bf16 v[0:15], v[136:139], v[132:135], v[0:15]
	s_waitcnt lgkmcnt(4)
	v_mfma_f32_32x32x16_bf16 v[96:111], v[128:131], v[140:143], v[96:111]
	v_mfma_f32_32x32x16_bf16 v[16:31], v[136:139], v[140:143], v[16:31]
	s_waitcnt lgkmcnt(2)
	v_mfma_f32_32x32x16_bf16 v[80:95], v[128:131], v[144:147], v[80:95]
	v_mfma_f32_32x32x16_bf16 v[32:47], v[136:139], v[144:147], v[32:47]
	s_waitcnt lgkmcnt(0)
	v_mfma_f32_32x32x16_bf16 v[64:79], v[128:131], v[148:151], v[64:79]
	v_mfma_f32_32x32x16_bf16 v[48:63], v[136:139], v[148:151], v[48:63]
	s_waitcnt vmcnt(0)
	s_add_u32 s30, s30, 0x50000
	s_addc_u32 s31, s31, 0
	s_cmp_eq_u32 s45, s38
	s_mov_b32 s8, s39
	s_barrier
	s_cbranch_scc1 .LBB0_383
	s_branch .Lat2_top_O

; #define SB() __builtin_amdgcn_sched_barrier(0)
; #define EXPACK(sc_, rbq_, p0_, p1_) do { float ps_ = 0.f; \
;                 _Pragma("unroll") for (int r = 0; r < 16; ++r) { sc_[r] = __builtin_amdgcn_exp2f(SHIFT ? sc_[r] - bound2 : sc_[r]); ps_ += sc_[r]; } \
;                 lsum[rbq_] += ps_; p0_ = pack8(sc_, 0); p1_ = pack8(sc_, 1); } while (0)
; #define BLOAD(B_, ks_) do { asm volatile("" : "+v"(v0l)); _Pragma("unroll") for (int cb = 0; cb < 4; ++cb) B_[cb] = BFRAG(ks_, cb); SB(); } while (0)
; #define PVMMA(B_, pA_, pB_) do { _Pragma("unroll") for (int cb = 0; cb < 4; ++cb) { o[0][cb] = MFMA32(pA_, B_[cb], o[0][cb]); o[1][cb] = MFMA32(pB_, B_[cb], o[1][cb]); } } while (0)
; template <bool SHIFT> DI void phase_attn2(const Params& p, const Grp& G, int layer, LAS unsigned char* lds, int tid, int wave, int lane, int vcu, bool dry) {
;     ...
;             {
;                 f32x16 s0, s1; bf16x8 pa00, pa01, pa10, pa11; bf16x8 kfs[4], qfs[4];
;                 CHAIN(s0, 0, 0, true, true); CHAIN(s1, 0, 1, false, true);
;                 EXPACK(s0, 0, pa00, pa01); EXPACK(s1, 1, pa10, pa11);
;                 SB();
;                 CHAIN(s1, 1, 1, true, false); CHAIN(s0, 1, 0, false, true);
;                 bf16x8 pb00, pb01, pb10, pb11; bf16x8 B[4];
;                 BLOAD(B, 0);
;                 PVMMA(B, pa00, pa10); EXPACK(s0, 0, pb00, pb01);
;                 SB();
;                 BLOAD(B, 1);
;                 PVMMA(B, pa01, pa11); EXPACK(s1, 1, pb10, pb11);
;                 SB();
;                 BLOAD(B, 2);
;                 PVMMA(B, pb00, pb10);
;                 SB();
;                 BLOAD(B, 3);
;                 PVMMA(B, pb01, pb11);
;                 SB();
;             }
.Lat2_body_O:
	s_waitcnt lgkmcnt(0)
	v_mfma_f32_32x32x16_bf16 v[144:159], v[128:131], v[132:135], 0
	v_mfma_f32_32x32x16_bf16 v[144:159], v[160:163], v[136:139], v[144:159]
	v_mfma_f32_32x32x16_bf16 v[144:159], v[166:169], v[140:143], v[144:159]
	v_mfma_f32_32x32x16_bf16 v[144:159], v[170:173], v[174:177], v[144:159]
	ds_read_b128 v[174:177], v222 offset:4096
	ds_read_b128 v[178:181], v222 offset:5120
	ds_read_b128 v[182:185], v222 offset:6144
	ds_read_b128 v[224:227], v222 offset:7168
	s_waitcnt lgkmcnt(0)
	v_mfma_f32_32x32x16_bf16 v[128:143], v[128:131], v[174:177], 0
	v_mfma_f32_32x32x16_bf16 v[128:143], v[160:163], v[178:181], v[128:143]
	v_mfma_f32_32x32x16_bf16 v[128:143], v[166:169], v[182:185], v[128:143]
	v_mfma_f32_32x32x16_bf16 v[128:143], v[170:173], v[224:227], v[128:143]
	ds_read_b128 v[170:173], v236 offset:40960
	ds_read_b128 v[228:231], v237 offset:40960
	ds_read_b128 v[232:235], v238 offset:40960
	v_exp_f32_e32 v144, v144
	v_exp_f32_e32 v145, v145
	v_exp_f32_e32 v146, v146
	v_exp_f32_e32 v147, v147
	v_exp_f32_e32 v148, v148
	v_exp_f32_e32 v149, v149
	v_exp_f32_e32 v150, v150
	v_exp_f32_e32 v188, v151
	v_exp_f32_e32 v208, v152
	v_exp_f32_e32 v206, v153
	v_exp_f32_e32 v204, v154
	v_exp_f32_e32 v202, v155
	v_exp_f32_e32 v200, v156
	v_exp_f32_e32 v198, v157
	v_exp_f32_e32 v196, v158
	v_exp_f32_e32 v190, v159
	v_exp_f32_e32 v189, v135
	v_add_f32_e32 v135, v145, v144
	v_exp_f32_e32 v128, v128
	v_exp_f32_e32 v129, v129
	v_exp_f32_e32 v130, v130
	v_exp_f32_e32 v131, v131
	v_exp_f32_e32 v132, v132
	v_exp_f32_e32 v133, v133
	v_exp_f32_e32 v134, v134
	v_add_f32_e32 v135, v146, v135
	v_add_f32_e32 v135, v147, v135
	v_add_f32_e32 v135, v148, v135
	v_add_f32_e32 v135, v149, v135
	v_cvt_pk_bf16_f32 v160, v144, v145
	v_cvt_pk_bf16_f32 v161, v146, v147
	v_cvt_pk_bf16_f32 v162, v148, v149
	v_cvt_pk_bf16_f32 v163, v150, v188
	v_exp_f32_e32 v209, v136
	v_exp_f32_e32 v207, v137
	v_exp_f32_e32 v205, v138
	v_exp_f32_e32 v203, v139
	v_exp_f32_e32 v201, v140
	v_exp_f32_e32 v199, v141
	v_exp_f32_e32 v197, v142
	v_exp_f32_e32 v191, v143
	v_add_f32_e32 v210, v150, v135
	v_cvt_pk_bf16_f32 v166, v128, v129
	v_cvt_pk_bf16_f32 v167, v130, v131
	v_cvt_pk_bf16_f32 v168, v132, v133
	v_cvt_pk_bf16_f32 v169, v134, v189
	ds_read_b128 v[144:147], v217 offset:40960
	v_add_f32_e32 v128, v129, v128
	v_add_f32_e32 v128, v130, v128
	v_add_f32_e32 v128, v131, v128
	v_add_f32_e32 v128, v132, v128
	v_add_f32_e32 v128, v133, v128
	v_add_f32_e32 v211, v134, v128
	s_waitcnt lgkmcnt(0)
	v_mfma_f32_32x32x16_bf16 v[128:143], v[144:147], v[174:177], 0
	v_mfma_f32_32x32x16_bf16 v[128:143], v[170:173], v[178:181], v[128:143]
	v_mfma_f32_32x32x16_bf16 v[128:143], v[228:231], v[182:185], v[128:143]
	v_mfma_f32_32x32x16_bf16 v[128:143], v[232:235], v[224:227], v[128:143]
	ds_read_b128 v[148:151], v222
	ds_read_b128 v[174:177], v222 offset:1024
	ds_read_b128 v[178:181], v222 offset:2048
	ds_read_b128 v[182:185], v222 offset:3072
	s_waitcnt lgkmcnt(0)
	v_mfma_f32_32x32x16_bf16 v[144:159], v[144:147], v[148:151], 0
	v_mfma_f32_32x32x16_bf16 v[144:159], v[170:173], v[174:177], v[144:159]
	v_mfma_f32_32x32x16_bf16 v[144:159], v[228:231], v[178:181], v[144:159]
	v_mfma_f32_32x32x16_bf16 v[144:159], v[232:235], v[182:185], v[144:159]
	s_nop 4
	ds_read_b64_tr_b16 v[170:171], v218 offset:49152
	ds_read_b64_tr_b16 v[172:173], v239 offset:51200
	ds_read_b64_tr_b16 v[174:175], v240 offset:49152
	ds_read_b64_tr_b16 v[176:177], v241 offset:51200
	ds_read_b64_tr_b16 v[178:179], v248 offset:49152
	ds_read_b64_tr_b16 v[180:181], v249 offset:51200
	ds_read_b64_tr_b16 v[182:183], v250 offset:49152
	ds_read_b64_tr_b16 v[184:185], v251 offset:51200
	v_exp_f32_e32 v144, v144
	s_waitcnt lgkmcnt(6)
	v_mfma_f32_32x32x16_bf16 v[112:127], v[160:163], v[170:173], v[112:127]
	v_exp_f32_e32 v145, v145
	v_exp_f32_e32 v146, v146
	v_exp_f32_e32 v147, v147
	v_exp_f32_e32 v148, v148
	v_exp_f32_e32 v149, v149
	v_mfma_f32_32x32x16_bf16 v[0:15], v[166:169], v[170:173], v[0:15]
	v_exp_f32_e32 v170, v151
	v_exp_f32_e32 v172, v154
	s_waitcnt lgkmcnt(4)
	v_mfma_f32_32x32x16_bf16 v[96:111], v[160:163], v[174:177], v[96:111]
	v_mfma_f32_32x32x16_bf16 v[16:31], v[166:169], v[174:177], v[16:31]
	v_exp_f32_e32 v174, v153
	v_exp_f32_e32 v176, v156
	s_waitcnt lgkmcnt(2)
	v_mfma_f32_32x32x16_bf16 v[80:95], v[160:163], v[178:181], v[80:95]
	v_mfma_f32_32x32x16_bf16 v[32:47], v[166:169], v[178:181], v[32:47]
	v_exp_f32_e32 v178, v155
	v_exp_f32_e32 v180, v158
	s_waitcnt lgkmcnt(0)
	v_mfma_f32_32x32x16_bf16 v[64:79], v[160:163], v[182:185], v[64:79]
	v_add_f32_e32 v160, v145, v144
	v_add_f32_e32 v160, v146, v160
	v_add_f32_e32 v160, v147, v160
	v_add_f32_e32 v160, v148, v160
	v_add_f32_e32 v186, v149, v160
	v_cvt_pk_bf16_f32 v144, v144, v145
	v_mfma_f32_32x32x16_bf16 v[48:63], v[166:169], v[182:185], v[48:63]
	v_exp_f32_e32 v166, v150
	v_exp_f32_e32 v168, v152
	v_exp_f32_e32 v182, v157
	v_exp_f32_e32 v184, v159
	v_cvt_pk_bf16_f32 v145, v146, v147
	v_cvt_pk_bf16_f32 v146, v148, v149
	s_nop 0
	ds_read_b64_tr_b16 v[160:161], v218 offset:53248
	ds_read_b64_tr_b16 v[162:163], v239 offset:55296
	ds_read_b64_tr_b16 v[156:157], v240 offset:53248
	ds_read_b64_tr_b16 v[158:159], v241 offset:55296
	ds_read_b64_tr_b16 v[152:153], v248 offset:53248
	ds_read_b64_tr_b16 v[154:155], v249 offset:55296
	ds_read_b64_tr_b16 v[148:149], v250 offset:53248
	ds_read_b64_tr_b16 v[150:151], v251 offset:55296
	v_exp_f32_e32 v223, v128
	v_exp_f32_e32 v224, v129
	v_exp_f32_e32 v225, v130
	v_exp_f32_e32 v226, v131
	v_exp_f32_e32 v227, v132
	v_add_f32_e32 v128, v224, v223
	v_exp_f32_e32 v228, v133
	v_exp_f32_e32 v167, v134
	v_exp_f32_e32 v171, v135
	v_cvt_pk_bf16_f32 v132, v208, v206
	v_cvt_pk_bf16_f32 v133, v204, v202
	v_cvt_pk_bf16_f32 v134, v200, v198
	v_cvt_pk_bf16_f32 v135, v196, v190
	v_add_f32_e32 v128, v225, v128
	v_exp_f32_e32 v169, v136
	v_exp_f32_e32 v175, v137
	v_exp_f32_e32 v173, v138
	v_exp_f32_e32 v179, v139
	v_cvt_pk_bf16_f32 v136, v209, v207
	v_cvt_pk_bf16_f32 v137, v205, v203
	v_cvt_pk_bf16_f32 v138, v201, v199
	v_cvt_pk_bf16_f32 v139, v197, v191
	v_add_f32_e32 v128, v226, v128
	v_add_f32_e32 v128, v227, v128
	v_add_f32_e32 v187, v228, v128
	v_pk_add_f32 v[128:129], v[188:189], v[210:211]
	s_waitcnt lgkmcnt(6)
; #define LAS __attribute__((address_space(3)))
; #define SB() __builtin_amdgcn_sched_barrier(0)
; #define EXPACK(sc_, rbq_, p0_, p1_) do { float ps_ = 0.f; \
;                 _Pragma("unroll") for (int r = 0; r < 16; ++r) { sc_[r] = __builtin_amdgcn_exp2f(SHIFT ? sc_[r] - bound2 : sc_[r]); ps_ += sc_[r]; } \
;                 lsum[rbq_] += ps_; p0_ = pack8(sc_, 0); p1_ = pack8(sc_, 1); } while (0)
; #define BLOAD(B_, ks_) do { asm volatile("" : "+v"(v0l)); _Pragma("unroll") for (int cb = 0; cb < 4; ++cb) B_[cb] = BFRAG(ks_, cb); SB(); } while (0)
; #define PVMMA(B_, pA_, pB_) do { _Pragma("unroll") for (int cb = 0; cb < 4; ++cb) { o[0][cb] = MFMA32(pA_, B_[cb], o[0][cb]); o[1][cb] = MFMA32(pB_, B_[cb], o[1][cb]); } } while (0)
; template <bool SHIFT> DI void phase_attn2(const Params& p, const Grp& G, int layer, LAS unsigned char* lds, int tid, int wave, int lane, int vcu, bool dry) {
;     ...
;         for (int t = 0; t < NT; ++t) {
;             unsigned dfl = doff0; asm volatile("" : "+v"(dfl));
;             if (t + 1 < NT) AT2_DMA(t + 1, (t + 1) & 1);
;             const LAS unsigned char* Kt = lds + (t & 1) * AT2_BUF; const LAS unsigned char* Vt = Kt + AT2_TILE;
;             int k0l = k0, v0l = v0; asm volatile("" : "+v"(k0l), "+v"(v0l));
;     ...
;                 PVMMA(B, pa00, pa10); EXPACK(s0, 0, pb00, pb01);
;                 SB();
;                 BLOAD(B, 1);
;                 PVMMA(B, pa01, pa11); EXPACK(s1, 1, pb10, pb11);
;                 SB();
;                 BLOAD(B, 2);
;                 PVMMA(B, pb00, pb10);
;                 SB();
;                 BLOAD(B, 3);
;                 PVMMA(B, pb01, pb11);
;                 SB();
;             }
;     ...
;             asm volatile("s_waitcnt vmcnt(0)" ::: "memory");
;             __syncthreads();
	v_mfma_f32_32x32x16_bf16 v[112:127], v[132:135], v[160:163], v[112:127]
	v_add_f32_e64 v128, v208, v128
	v_add_f32_e64 v129, v209, v129
	v_exp_f32_e32 v177, v140
	v_pk_add_f32 v[128:129], v[206:207], v[128:129]
	v_exp_f32_e32 v183, v141
	v_pk_add_f32 v[128:129], v[204:205], v[128:129]
	v_exp_f32_e32 v181, v142
	v_pk_add_f32 v[128:129], v[202:203], v[128:129]
	s_waitcnt lgkmcnt(4)
	v_mfma_f32_32x32x16_bf16 v[96:111], v[132:135], v[156:159], v[96:111]
	v_exp_f32_e32 v185, v143
	v_pk_add_f32 v[128:129], v[200:201], v[128:129]
	v_cvt_pk_bf16_f32 v147, v166, v170
	v_pk_add_f32 v[128:129], v[198:199], v[128:129]
	v_cvt_pk_bf16_f32 v130, v176, v182
	v_pk_add_f32 v[128:129], v[196:197], v[128:129]
	v_cvt_pk_bf16_f32 v131, v180, v184
	s_waitcnt lgkmcnt(2)
	v_mfma_f32_32x32x16_bf16 v[80:95], v[132:135], v[152:155], v[80:95]
	v_add_f32_e64 v128, v190, v128
	v_add_f32_e64 v129, v191, v129
	v_add_f32_e64 v140, v164, v128
	v_add_f32_e64 v141, v165, v129
	v_cvt_pk_bf16_f32 v128, v168, v174
	v_cvt_pk_bf16_f32 v129, v172, v178
	s_waitcnt lgkmcnt(0)
	v_mfma_f32_32x32x16_bf16 v[64:79], v[132:135], v[148:151], v[64:79]
	v_add_f32_e64 v132, v166, v186
	v_add_f32_e64 v133, v167, v187
	v_cvt_pk_bf16_f32 v134, v227, v228
	v_add_f32_e64 v132, v170, v132
	v_add_f32_e64 v133, v171, v133
	v_cvt_pk_bf16_f32 v135, v167, v171
	v_pk_add_f32 v[132:133], v[168:169], v[132:133]
	s_nop 0
	v_pk_add_f32 v[132:133], v[174:175], v[132:133]
	v_mfma_f32_32x32x16_bf16 v[0:15], v[136:139], v[160:163], v[0:15]
	v_add_f32_e64 v132, v172, v132
	v_add_f32_e64 v133, v173, v133
	v_add_f32_e64 v132, v178, v132
	v_add_f32_e64 v133, v179, v133
	v_add_f32_e64 v132, v176, v132
	v_add_f32_e64 v133, v177, v133
	v_pk_add_f32 v[132:133], v[182:183], v[132:133]
	v_mfma_f32_32x32x16_bf16 v[16:31], v[136:139], v[156:159], v[16:31]
	v_add_f32_e64 v132, v180, v132
	v_add_f32_e64 v133, v181, v133
	v_add_f32_e64 v142, v184, v132
	v_add_f32_e64 v143, v185, v133
	v_cvt_pk_bf16_f32 v132, v223, v224
	v_cvt_pk_bf16_f32 v133, v225, v226
	v_mfma_f32_32x32x16_bf16 v[32:47], v[136:139], v[152:155], v[32:47]
	v_mfma_f32_32x32x16_bf16 v[48:63], v[136:139], v[148:151], v[48:63]
	v_cvt_pk_bf16_f32 v136, v169, v175
	v_cvt_pk_bf16_f32 v137, v173, v179
	v_cvt_pk_bf16_f32 v138, v177, v183
	v_cvt_pk_bf16_f32 v139, v181, v185
	s_nop 0
	ds_read_b64_tr_b16 v[148:149], v218 offset:57344
	ds_read_b64_tr_b16 v[150:151], v239 offset:59392
	ds_read_b64_tr_b16 v[152:153], v240 offset:57344
	ds_read_b64_tr_b16 v[154:155], v241 offset:59392
	ds_read_b64_tr_b16 v[156:157], v248 offset:57344
	ds_read_b64_tr_b16 v[158:159], v249 offset:59392
	ds_read_b64_tr_b16 v[160:161], v250 offset:57344
	ds_read_b64_tr_b16 v[162:163], v251 offset:59392
	s_waitcnt lgkmcnt(6)
	v_mfma_f32_32x32x16_bf16 v[112:127], v[144:147], v[148:151], v[112:127]
	v_add_f32_e64 v164, v140, v142
	v_add_f32_e64 v165, v141, v143
	v_mfma_f32_32x32x16_bf16 v[0:15], v[132:135], v[148:151], v[0:15]
	s_waitcnt lgkmcnt(4)
	v_mfma_f32_32x32x16_bf16 v[96:111], v[144:147], v[152:155], v[96:111]
	v_mfma_f32_32x32x16_bf16 v[16:31], v[132:135], v[152:155], v[16:31]
	s_waitcnt lgkmcnt(2)
	v_mfma_f32_32x32x16_bf16 v[80:95], v[144:147], v[156:159], v[80:95]
	v_mfma_f32_32x32x16_bf16 v[32:47], v[132:135], v[156:159], v[32:47]
	s_waitcnt lgkmcnt(0)
	v_mfma_f32_32x32x16_bf16 v[64:79], v[144:147], v[160:163], v[64:79]
	v_mfma_f32_32x32x16_bf16 v[48:63], v[132:135], v[160:163], v[48:63]
	s_nop 0
	ds_read_b64_tr_b16 v[132:133], v218 offset:61440
	ds_read_b64_tr_b16 v[134:135], v239 offset:63488
	ds_read_b64_tr_b16 v[140:141], v240 offset:61440
	ds_read_b64_tr_b16 v[142:143], v241 offset:63488
	ds_read_b64_tr_b16 v[144:145], v248 offset:61440
	ds_read_b64_tr_b16 v[146:147], v249 offset:63488
	ds_read_b64_tr_b16 v[148:149], v250 offset:61440
	ds_read_b64_tr_b16 v[150:151], v251 offset:63488
	s_waitcnt lgkmcnt(6)
	v_mfma_f32_32x32x16_bf16 v[112:127], v[128:131], v[132:135], v[112:127]
	v_mfma_f32_32x32x16_bf16 v[0:15], v[136:139], v[132:135], v[0:15]
	s_waitcnt lgkmcnt(4)
	v_mfma_f32_32x32x16_bf16 v[96:111], v[128:131], v[140:143], v[96:111]
	v_mfma_f32_32x32x16_bf16 v[16:31], v[136:139], v[140:143], v[16:31]
	s_waitcnt lgkmcnt(2)
	v_mfma_f32_32x32x16_bf16 v[80:95], v[128:131], v[144:147], v[80:95]
	v_mfma_f32_32x32x16_bf16 v[32:47], v[136:139], v[144:147], v[32:47]
	s_waitcnt lgkmcnt(0)
	v_mfma_f32_32x32x16_bf16 v[64:79], v[128:131], v[148:151], v[64:79]
	v_mfma_f32_32x32x16_bf16 v[48:63], v[136:139], v[148:151], v[48:63]
	s_waitcnt vmcnt(0)
	s_add_u32 s30, s30, 0x50000
	s_addc_u32 s31, s31, 0
	s_cmp_eq_u32 s45, s38
	s_mov_b32 s8, s39
	s_barrier
	s_cbranch_scc1 .LBB0_383
	s_branch .LBB0_379
.Lat2_top_O:
	ds_read_b128 v[128:131], v217 offset:32768
	ds_read_b128 v[160:163], v236 offset:32768
	ds_read_b128 v[166:169], v237 offset:32768
	ds_read_b128 v[170:173], v238 offset:32768
	ds_read_b128 v[132:135], v222
	ds_read_b128 v[136:139], v222 offset:1024
	ds_read_b128 v[140:143], v222 offset:2048
	ds_read_b128 v[174:177], v222 offset:3072
	s_add_i32 s38, s38, 1
	s_cmp_lt_u32 s38, s45
	s_mov_b64 s[0:1], -1
	s_cbranch_scc1 .Lat2_skip_O
	s_add_i32 s39, s8, 0x8000
	s_mov_b64 s[0:1], 0
